# P0: odd waves do the row loop before the W1GU conversion loop (even waves keep the order), drain between the two on odd waves
# baseline (speedup 1.0000x reference)
; #define LAS __attribute__((address_space(3)))
; __device__ __forceinline__ void tr_load(const TrD& d, int lane, f32x4 (&v)[8], float (&gg)[8]) {
;     const int nblk = d.N / 32, kb = d.item / nblk, nb = d.item % nblk, k0 = 64 * kb, n0 = 32 * nb;
;     const int row8 = lane >> 3, c4 = lane & 7;
; #pragma unroll
;     for (int i = 0; i < 8; ++i) v[i] = __builtin_nontemporal_load((const f32x4*)(d.W + (size_t)(k0 + 8 * i + row8) * d.N + n0 + 4 * c4));
; #pragma unroll
;     for (int i = 0; i < 8; ++i) { const float* gp = d.gk ? d.gk + k0 + 8 * i + row8 : d.W; const float x = __builtin_nontemporal_load(gp); gg[i] = d.gk ? x : 1.f; }
; }
; __device__ __forceinline__ void p0_prologue(const Ptrs& P, LAS unsigned char* lds, int gw, int NGW, int wave, int lane, int gtid, int NGT) {
;     LAS float* scr = (LAS float*)(lds + wave * 16384);
;     constexpr int I_GU = 16 * 88;
;     tr_loop([&](int it) { return it < I_GU ? TrD{P.w1g, P.W1GU, P.g1a, D, DFF, 1, it} : TrD{P.w1u, P.W1GU, P.g1a, D, DFF, 2, it - I_GU}; }, gw, 2 * I_GU, NGW, lane, scr);
.LBB0_11:
	s_or_b64 exec, exec, s[2:3]
	s_load_dwordx16 s[72:87], s[0:1], 0x0
	s_load_dwordx16 s[4:19], s[0:1], 0x40
	v_and_b32_e32 v162, 63, v0
	v_lshlrev_b32_e32 v163, 2, v0
	v_and_b32_e32 v1, 7, v0
	s_waitcnt lgkmcnt(0)
	v_writelane_b32 v254, s4, 18
	s_nop 1
	v_writelane_b32 v254, s5, 19
	v_writelane_b32 v254, s6, 20
	v_writelane_b32 v254, s7, 21
	v_writelane_b32 v254, s8, 22
	v_writelane_b32 v254, s9, 23
	v_writelane_b32 v254, s10, 24
	v_writelane_b32 v254, s11, 25
	v_writelane_b32 v254, s12, 26
	v_writelane_b32 v254, s13, 27
	v_writelane_b32 v254, s14, 28
	v_writelane_b32 v254, s15, 29
	v_writelane_b32 v254, s16, 30
	v_writelane_b32 v254, s17, 31
	v_writelane_b32 v254, s18, 32
	v_writelane_b32 v254, s19, 33
	s_nop 0
	v_readlane_b32 s0, v254, 12
	s_lshl_b32 s69, s0, 3
	v_readlane_b32 s0, v254, 0
	s_lshr_b32 s1, s0, 6
	v_readlane_b32 s0, v254, 11
	s_lshl_b32 s0, s0, 3
	s_add_i32 s16, s1, s0
	v_writelane_b32 v254, s1, 34
	s_add_u32 s4, s90, 0x100000
	s_mov_b32 s0, s16
	s_addc_u32 s5, s91, 0
	v_writelane_b32 v254, s0, 35
	s_nop 0
	v_writelane_b32 v254, s1, 36
	s_bitcmp1_b32 s1, 0
	s_cbranch_scc0 .Lp0_tr
	s_mov_b64 s[98:99], s[82:83]
	s_mov_b64 s[100:101], s[86:87]
	s_branch .LBB0_17
.Lp0_tr:
	s_cmpk_gt_i32 s16, 0xaff
	s_cbranch_scc1 .Lp0_tr_done
	v_readlane_b32 s0, v254, 34
	s_lshl_b32 s0, s0, 14
	s_add_i32 s14, s0, 0
	s_add_i32 s0, s16, 0xfffffa80
	s_cmpk_lt_i32 s16, 0x580
	s_cselect_b32 s27, s16, s0
	v_readlane_b32 s36, v254, 18
	v_readlane_b32 s37, v254, 19
	s_mul_hi_i32 s2, s27, 0x2e8ba2e9
	s_cselect_b32 s26, 1, 2
	s_cselect_b32 s1, s87, s37
	s_cselect_b32 s0, s86, s36
	s_lshr_b32 s3, s2, 31
	s_ashr_i32 s2, s2, 4
	s_add_i32 s2, s2, s3
	s_mul_i32 s3, s2, 0x58
	s_sub_i32 s3, s27, s3
	s_lshl_b32 s6, s2, 6
	v_lshrrev_b32_e32 v73, 3, v162
	s_lshl_b32 s2, s3, 5
	v_or_b32_e32 v14, s6, v73
	s_ashr_i32 s3, s2, 31
	s_movk_i32 s22, 0x2c00
	v_mov_b64_e32 v[2:3], s[0:1]
	v_or_b32_e32 v12, 32, v14
	v_and_b32_e32 v34, 28, v163
	s_lshl_b64 s[2:3], s[2:3], 2
	v_mad_i64_i32 v[12:13], s[8:9], v12, s22, v[2:3]
	v_mov_b32_e32 v67, 0
	v_lshlrev_b32_e32 v66, 2, v34
	v_lshl_add_u64 v[12:13], v[12:13], 0, s[2:3]
	v_lshl_add_u64 v[26:27], v[12:13], 0, v[66:67]
	v_or_b32_e32 v12, 40, v14
	v_mad_i64_i32 v[12:13], s[8:9], v12, s22, v[2:3]
	v_lshl_add_u64 v[12:13], v[12:13], 0, s[2:3]
	v_lshl_add_u64 v[28:29], v[12:13], 0, v[66:67]
	v_or_b32_e32 v12, 48, v14
	v_mad_i64_i32 v[12:13], s[8:9], v12, s22, v[2:3]
	v_lshl_add_u64 v[12:13], v[12:13], 0, s[2:3]
	v_or_b32_e32 v6, 8, v14
	v_or_b32_e32 v8, 16, v14
	v_or_b32_e32 v10, 24, v14
	v_lshl_add_u64 v[30:31], v[12:13], 0, v[66:67]
	v_or_b32_e32 v12, 56, v14
	v_mad_i64_i32 v[4:5], s[8:9], v14, s22, v[2:3]
	v_mad_i64_i32 v[6:7], s[8:9], v6, s22, v[2:3]
	v_mad_i64_i32 v[8:9], s[8:9], v8, s22, v[2:3]
	v_mad_i64_i32 v[10:11], s[8:9], v10, s22, v[2:3]
	v_mad_i64_i32 v[2:3], s[8:9], v12, s22, v[2:3]
	s_cmp_eq_u64 s[82:83], 0
	v_lshl_add_u64 v[4:5], v[4:5], 0, s[2:3]
	v_lshl_add_u64 v[6:7], v[6:7], 0, s[2:3]
	v_lshl_add_u64 v[8:9], v[8:9], 0, s[2:3]
	v_lshl_add_u64 v[10:11], v[10:11], 0, s[2:3]
	v_lshl_add_u64 v[2:3], v[2:3], 0, s[2:3]
	s_cselect_b64 s[2:3], -1, 0
	s_ashr_i32 s7, s6, 31
	s_lshl_b64 s[6:7], s[6:7], 2
	s_add_u32 s6, s82, s6
	v_lshl_add_u64 v[4:5], v[4:5], 0, v[66:67]
	v_lshl_add_u64 v[6:7], v[6:7], 0, v[66:67]
	v_lshl_add_u64 v[8:9], v[8:9], 0, v[66:67]
	v_lshl_add_u64 v[10:11], v[10:11], 0, v[66:67]
	v_lshl_add_u64 v[36:37], v[2:3], 0, v[66:67]
	s_addc_u32 s7, s83, s7
	v_lshlrev_b32_e32 v66, 2, v73
	v_mov_b32_e32 v14, s1
	v_lshl_add_u64 v[2:3], s[6:7], 0, v[66:67]
	v_mov_b32_e32 v15, s0
	v_cndmask_b32_e64 v13, v3, v14, s[2:3]
	v_cndmask_b32_e64 v12, v2, v15, s[2:3]
	global_load_dword v35, v[12:13], off nt
	v_lshl_add_u64 v[12:13], v[2:3], 0, 32
	v_cndmask_b32_e64 v13, v13, v14, s[2:3]
	v_cndmask_b32_e64 v12, v12, v15, s[2:3]
	global_load_dword v38, v[12:13], off nt
	v_lshl_add_u64 v[12:13], v[2:3], 0, 64
	v_cndmask_b32_e64 v13, v13, v14, s[2:3]
	v_cndmask_b32_e64 v12, v12, v15, s[2:3]
	s_mov_b64 s[0:1], 0x60
	global_load_dword v39, v[12:13], off nt
	v_lshl_add_u64 v[12:13], v[2:3], 0, s[0:1]
	v_cndmask_b32_e64 v13, v13, v14, s[2:3]
	v_cndmask_b32_e64 v12, v12, v15, s[2:3]
	s_mov_b64 s[6:7], 0x80
	global_load_dword v40, v[12:13], off nt
	v_lshl_add_u64 v[12:13], v[2:3], 0, s[6:7]
	v_cndmask_b32_e64 v13, v13, v14, s[2:3]
	v_cndmask_b32_e64 v12, v12, v15, s[2:3]
	s_mov_b64 s[8:9], 0xa0
	global_load_dword v41, v[12:13], off nt
	v_lshl_add_u64 v[12:13], v[2:3], 0, s[8:9]
	v_cndmask_b32_e64 v13, v13, v14, s[2:3]
	v_cndmask_b32_e64 v12, v12, v15, s[2:3]
	s_mov_b64 s[10:11], 0xc0
	global_load_dword v42, v[12:13], off nt
	v_lshl_add_u64 v[12:13], v[2:3], 0, s[10:11]
	v_cndmask_b32_e64 v13, v13, v14, s[2:3]
	v_cndmask_b32_e64 v12, v12, v15, s[2:3]
	global_load_dword v43, v[12:13], off nt
	s_mov_b64 s[12:13], 0xe0
	v_lshl_add_u64 v[2:3], v[2:3], 0, s[12:13]
	v_cndmask_b32_e64 v3, v3, v14, s[2:3]
	v_cndmask_b32_e64 v2, v2, v15, s[2:3]
	global_load_dword v44, v[2:3], off nt
	global_load_dwordx4 v[22:25], v[4:5], off nt
	global_load_dwordx4 v[18:21], v[6:7], off nt
	global_load_dwordx4 v[14:17], v[8:9], off nt
	s_nop 0
	global_load_dwordx4 v[10:13], v[10:11], off nt
	s_nop 0
	global_load_dwordx4 v[6:9], v[26:27], off nt
	global_load_dwordx4 v[2:5], v[28:29], off nt
	s_nop 0
	global_load_dwordx4 v[30:33], v[30:31], off nt
	s_nop 0
	global_load_dwordx4 v[26:29], v[36:37], off nt
	v_mul_u32_u24_e32 v37, 0x420, v1
	v_mul_u32_u24_e32 v36, 0x84, v73
	v_add3_u32 v79, s14, v37, v66
	v_lshl_add_u64 v[68:69], s[82:83], 0, v[66:67]
	v_lshlrev_b32_e32 v66, 2, v34
	v_lshlrev_b32_e32 v34, 3, v1
	v_or_b32_e32 v75, 8, v73
	v_or_b32_e32 v77, 16, v73
	v_or_b32_e32 v81, 24, v73
	s_movk_i32 s24, 0x7fff
	s_mov_b32 s25, 0xffff0000
	v_lshlrev_b32_e32 v70, 1, v34
	s_mov_b32 s28, s16
	v_readlane_b32 s38, v254, 20
	v_readlane_b32 s39, v254, 21
	v_readlane_b32 s40, v254, 22
	v_readlane_b32 s41, v254, 23
	v_readlane_b32 s42, v254, 24
	v_readlane_b32 s43, v254, 25
	v_readlane_b32 s44, v254, 26
	v_readlane_b32 s45, v254, 27
	v_readlane_b32 s46, v254, 28
	v_readlane_b32 s47, v254, 29
	v_readlane_b32 s48, v254, 30
	v_readlane_b32 s49, v254, 31
	v_readlane_b32 s50, v254, 32
	v_readlane_b32 s51, v254, 33
	s_waitcnt vmcnt(15)
	v_cndmask_b32_e64 v86, v35, 1.0, s[2:3]
	v_lshl_add_u32 v35, v1, 4, s14
	v_readlane_b32 s14, v254, 12
	v_add_u32_e32 v83, v35, v36
	s_waitcnt vmcnt(14)
	v_cndmask_b32_e64 v84, v38, 1.0, s[2:3]
	s_lshl_b32 s23, s14, 4
	s_waitcnt vmcnt(13)
	v_cndmask_b32_e64 v82, v39, 1.0, s[2:3]
	s_waitcnt vmcnt(12)
	v_cndmask_b32_e64 v80, v40, 1.0, s[2:3]
	s_waitcnt vmcnt(11)
	v_cndmask_b32_e64 v78, v41, 1.0, s[2:3]
	s_waitcnt vmcnt(10)
	v_cndmask_b32_e64 v76, v42, 1.0, s[2:3]
	s_waitcnt vmcnt(8)
	v_cndmask_b32_e64 v72, v44, 1.0, s[2:3]
	v_cndmask_b32_e64 v74, v43, 1.0, s[2:3]
	s_branch .LBB0_14

; #define LAS __attribute__((address_space(3)))
; __device__ __forceinline__ unsigned pk2(float lo, float hi) { return f2bf(lo) | (f2bf(hi) << 16); }
; __device__ __forceinline__ void p0_prologue(const Ptrs& P, LAS unsigned char* lds, int gw, int NGW, int wave, int lane, int gtid, int NGT) {
;     LAS float* scr = (LAS float*)(lds + wave * 16384);
;     constexpr int I_GU = 16 * 88;
;     tr_loop([&](int it) { return it < I_GU ? TrD{P.w1g, P.W1GU, P.g1a, D, DFF, 1, it} : TrD{P.w1u, P.W1GU, P.g1a, D, DFF, 2, it - I_GU}; }, gw, 2 * I_GU, NGW, lane, scr);
;     {
;         auto ld = [&](int r, f32x4 (&v)[4]) {
;             const f32x4* x = (const f32x4*)(r < MP ? P.xp + (size_t)r * D : P.xs + (size_t)(r - MP) * D);
; #pragma unroll
;             for (int j = 0; j < 4; ++j) v[j] = __builtin_nontemporal_load(x + lane + 64 * j); };
;         auto fin = [&](int r, const f32x4 (&v)[4]) {
;             float ss = 0.f;
; #pragma unroll
;             for (int j = 0; j < 4; ++j) ss += v[j][0] * v[j][0] + v[j][1] * v[j][1] + v[j][2] * v[j][2] + v[j][3] * v[j][3];
;             const float rstd = 1.f / sqrtf(wave_sum(ss) * (1.f / D) + EPS);
;             if (lane == 0) P.RS[r] = rstd;
;             uint2* o = (uint2*)(P.XN + (size_t)r * D);
; #pragma unroll
;             for (int j = 0; j < 4; ++j) o[lane + 64 * j] = make_uint2(pk2(v[j][0], v[j][1]), pk2(v[j][2], v[j][3])); };
;         int r = gw;
;         if (r < M) {
;             f32x4 v0[4], v1[4];
;             ld(r, v0);
;             for (;;) {
;                 { const int rn = r + NGW; const bool more = rn < M; ld(more ? rn : r, v1); __builtin_amdgcn_sched_barrier(0); fin(r, v0); if (!more) break; r = rn; }
.LBB0_16:
.Lp0_tr_done:
	v_readlane_b32 s16, v254, 35
	v_readlane_b32 s17, v254, 34
	s_bitcmp1_b32 s17, 0
	v_readlane_b32 s17, v254, 36
	s_cbranch_scc0 .LBB0_17
	s_add_u32 s82, s90, 0x2e100000
	s_addc_u32 s83, s91, 0
	v_readlane_b32 s87, v254, 12
	v_readlane_b32 s86, v254, 11
	s_branch .LBB0_30

; __device__ __forceinline__ void p0_prologue(const Ptrs& P, LAS unsigned char* lds, int gw, int NGW, int wave, int lane, int gtid, int NGT) {
;     ...
;         int r = gw;
;         if (r < M) {
;             f32x4 v0[4], v1[4];
;             ld(r, v0);
;             for (;;) {
;                 { const int rn = r + NGW; const bool more = rn < M; ld(more ? rn : r, v1); __builtin_amdgcn_sched_barrier(0); fin(r, v0); if (!more) break; r = rn; }
;                 { const int rn = r + NGW; const bool more = rn < M; ld(more ? rn : r, v0); __builtin_amdgcn_sched_barrier(0); fin(r, v1); if (!more) break; r = rn; }
;             }
.Lp0_rows_done:
	v_readlane_b32 s0, v254, 34
	s_bitcmp1_b32 s0, 0
	s_cbranch_scc0 .LBB0_30
	s_waitcnt vmcnt(0) lgkmcnt(0)
	s_mov_b64 s[82:83], s[98:99]
	s_mov_b64 s[86:87], s[100:101]
	v_readlane_b32 s16, v254, 35
	s_branch .Lp0_tr
